# 1.04x version plus a G==256 guard on the gMLP unit rebalance (no A0 change)
# baseline (speedup 1.0000x reference)
.LBB0_966:
	v_readlane_b32 s0, v255, 13
	v_readlane_b32 s1, v255, 14
	s_and_b64 s[0:1], s[0:1], exec
	s_movk_i32 s0, 0x4200
	s_cselect_b32 s2, 0x4000, s0
	s_lshr_b32 s8, s2, 5
	s_ashr_i32 s3, s3, 6
	v_readlane_b32 s0, v254, 46
	s_cmp_ge_i32 s0, s8
	s_barrier
	s_cbranch_scc1 .LBB0_969
	v_lshrrev_b32_e32 v5, 4, v233
	v_lshlrev_b32_e32 v0, 4, v234
	s_add_u32 s0, s10, 0x9900000
	v_readlane_b32 s4, v255, 8
	v_ashrrev_i32_e32 v36, 2, v234
	v_and_b32_e32 v2, 48, v0
	v_lshlrev_b32_e32 v0, 5, v5
	s_movk_i32 s6, 0x90
	s_addc_u32 s1, s11, 0
	s_lshl_b32 s9, s4, 9
	v_and_b32_e32 v3, 15, v234
	v_lshl_add_u64 v[20:21], v[130:131], 0, v[0:1]
	v_mul_lo_u32 v0, v36, s6
	v_lshlrev_b32_e32 v6, 1, v2
	s_add_u32 s4, s10, 0x90c0000
	v_lshl_or_b32 v18, s3, 4, v3
	v_lshlrev_b32_e32 v4, 2, v5
	v_add3_u32 v37, 0, v0, v6
	v_lshlrev_b32_e32 v0, 1, v3
	v_mul_u32_u24_e32 v3, 0x480, v5
	s_addc_u32 s5, s11, 0
	v_ashrrev_i32_e32 v19, 31, v18
	v_add3_u32 v38, 0, v0, v3
	v_lshlrev_b32_e32 v0, 1, v2
	v_lshlrev_b32_e32 v22, 1, v4
	v_readlane_b32 s14, v254, 50
	v_readlane_b32 s15, v254, 46
	s_mov_b32 s100, s42
	s_mov_b32 s101, s79
	s_cmpk_eq_i32 s8, 0x210
	s_cbranch_scc0 .Lgm_keep
	s_cmpk_lg_i32 s42, 0x100
	s_cbranch_scc1 .Lgm_keep
	s_cmp_lt_u32 s72, 16
	s_cbranch_scc1 .LBB0_969
	s_sub_i32 s15, s72, 16
	s_lshl_b32 s14, s15, 5
	s_movk_i32 s100, 0xf0
	s_movk_i32 s101, 0x1e00
